# speedup vs baseline: 1.0201x; 1.0051x over previous
; __device__ void nsa_item(const Params& p, int qb, int g, char* smem) {
;     ...
;   f32x16 o[4] = {};
;     ...
;     float m = -1e30f, l = 0.f;
;     nsa_pass<0, false>(p, L, q0, g, nct - cfirst, cfirst, smem, qr, m, l, 0.f, 0.f, o);
;     l = half_swap_sum(l);
;     const float off = (l > 0.f) ? m + log2f(l) : 0.f;
;     nsa_pass<0, true>(p, L, q0, g, nct - cfirst, cfirst, smem, qr, m, l, off, gate0, o);
.LBB0_273:
	v_mov_b32_e32 v69, v68
	v_mov_b32_e32 v35, 0
	v_and_b32_e32 v2, 63, v142
	v_permlane32_swap_b32_e32 v68, v69
	s_andn2_b64 vcc, exec, s[10:11]
	v_mov_b32_e32 v34, v35
	v_mov_b32_e32 v33, v35
	v_mov_b32_e32 v32, v35
	v_mov_b32_e32 v31, v35
	v_mov_b32_e32 v30, v35
	v_mov_b32_e32 v29, v35
	v_mov_b32_e32 v28, v35
	v_mov_b32_e32 v27, v35
	v_mov_b32_e32 v26, v35
	v_mov_b32_e32 v25, v35
	v_mov_b32_e32 v24, v35
	v_mov_b32_e32 v23, v35
	v_mov_b32_e32 v22, v35
	v_mov_b32_e32 v21, v35
	v_mov_b32_e32 v20, v35
	v_mov_b32_e32 v51, v35
	v_mov_b32_e32 v50, v35
	v_mov_b32_e32 v49, v35
	v_mov_b32_e32 v48, v35
	v_mov_b32_e32 v47, v35
	v_mov_b32_e32 v46, v35
	v_mov_b32_e32 v45, v35
	v_mov_b32_e32 v44, v35
	v_mov_b32_e32 v43, v35
	v_mov_b32_e32 v42, v35
	v_mov_b32_e32 v41, v35
	v_mov_b32_e32 v40, v35
	v_mov_b32_e32 v39, v35
	v_mov_b32_e32 v38, v35
	v_mov_b32_e32 v37, v35
	v_mov_b32_e32 v36, v35
	v_mov_b32_e32 v67, v35
	v_mov_b32_e32 v66, v35
	v_mov_b32_e32 v65, v35
	v_mov_b32_e32 v64, v35
	v_mov_b32_e32 v63, v35
	v_mov_b32_e32 v62, v35
	v_mov_b32_e32 v61, v35
	v_mov_b32_e32 v60, v35
	v_mov_b32_e32 v59, v35
	v_mov_b32_e32 v58, v35
	v_mov_b32_e32 v57, v35
	v_mov_b32_e32 v56, v35
	v_mov_b32_e32 v55, v35
	v_mov_b32_e32 v54, v35
	v_mov_b32_e32 v53, v35
	v_mov_b32_e32 v52, v35
	v_mov_b32_e32 v19, v35
	v_mov_b32_e32 v18, v35
	v_mov_b32_e32 v17, v35
	v_mov_b32_e32 v16, v35
	v_mov_b32_e32 v15, v35
	v_mov_b32_e32 v14, v35
	v_mov_b32_e32 v13, v35
	v_mov_b32_e32 v12, v35
	v_mov_b32_e32 v11, v35
	v_mov_b32_e32 v10, v35
	v_mov_b32_e32 v9, v35
	v_mov_b32_e32 v8, v35
	v_mov_b32_e32 v7, v35
	v_mov_b32_e32 v6, v35
	v_mov_b32_e32 v5, v35
	v_mov_b32_e32 v4, v35
	s_cbranch_vccnz .LBB0_303
; __device__ __forceinline__ int v_rd_base(int lane) { return ((lane & 3) << 3) | (((lane >> 2) & 3) << 6) | (((lane >> 4) & 1) << 5) | (((lane >> 5) & 1) << 8); }
; template <int MODE, bool PB>
; __device__ __forceinline__ void nsa_pass(const Params& p, const LaneId& L, int q0, int g, int ntiles, int first, char* smem, const bf16x8* qr,
;                                          float& m, float& l, float off, float gate0, f32x16* o) {
;     ...
;   const int vb0 = (int)(uintptr_t)(smem + NSA_V0) + v_rd_base(L.lane);
;   { const int row = tile_row(0); dma_k(Kg + (long)row * ld, ld, smem + NSA_K0, L.tid); if (PB) dma_v(Vg + (long)row * ld, ld, smem + NSA_V0, L.tid); }
; #pragma unroll 1
;   for (int i = 0; i < ntiles; ++i) {
;     const int row = tile_row(i), buf = i & 1;
;     char* Kl = smem + NSA_K0 + buf * 16384;
;     asm volatile("s_waitcnt vmcnt(0)" ::: "memory");
;     __syncthreads();
;     if (i + 1 < ntiles) { const int rn = tile_row(i + 1); dma_k(Kg + (long)rn * ld, ld, smem + NSA_K0 + (buf ^ 1) * 16384, L.tid); if (PB) dma_v(Vg + (long)rn * ld, ld, smem + NSA_V0 + (buf ^ 1) * 16384, L.tid); }
;     int pb, st, lo, hl; float badd = 0.f;
;     if (MODE == 0) { pb = 16 * row + 31; st = 16; lo = NEG; hl = (L.tq - pb) >> 4; }
;     else if (MODE == 1) { const int j = row >> 6; pb = row; st = 1; lo = NEG; const bool fl = ((mysel[j >> 5] >> (j & 31)) & 1u) != 0u;
;       if (row == q0) hl = fl ? (L.tq - pb) : NEG; else { hl = 1000; badd = fl ? 0.f : -INFINITY; } }
;     else { pb = row; st = 1; lo = L.tq - 512 - pb; hl = L.tq - pb; }
;     if (!PB) { f32x16 p0, p1; nsa_scores(p0, p1, Kl, qr, L.r32, L.hi, L.sl2, L.tq, pb, st, lo, hl, badd); stats_update(p0, p1, m, l); }
;     else {
;       constexpr float C = 0.08838834764831845f * LOG2E;
;       const float A1 = L.sl2 * (float)st; const float B1 = L.sl2 * (float)(pb - L.tq) + A1 * (float)(4 * L.hi) + badd;
;       const int lo2 = lo - 4 * L.hi, hl2 = hl - 4 * L.hi;
;       const bool nomask = __all(lo2 < 0 && hl2 >= 63);
;       float* impq = imp + (L.wid * 8 + L.qi) * IMP_LD + (row >> 2) + L.hi;
; __device__ void nsa_item(const Params& p, int qb, int g, char* smem) {
;     ...
;     l = half_swap_sum(l);
;     const float off = (l > 0.f) ? m + log2f(l) : 0.f;
;     nsa_pass<0, true>(p, L, q0, g, nct - cfirst, cfirst, smem, qr, m, l, off, gate0, o);
	v_add_f32_e32 v5, v68, v69
	s_mov_b32 s3, 0x800000
	v_cmp_gt_f32_e32 vcc, s3, v5
	s_waitcnt vmcnt(0)
	v_lshlrev_b32_e32 v7, 16, v82
	v_mul_f32_e32 v7, 0xbfb8aa3b, v7
	v_cndmask_b32_e64 v6, 0, 32, vcc
	v_ldexp_f32 v6, v5, v6
	v_exp_f32_e32 v7, v7
	v_log_f32_e32 v6, v6
	v_cndmask_b32_e32 v8, 0, v184, vcc
	v_cmp_lt_f32_e32 vcc, 0, v5
	v_add_f32_e32 v7, 1.0, v7
	v_sub_f32_e32 v6, v6, v8
	v_div_scale_f32 v8, s[10:11], v7, v7, 1.0
	v_rcp_f32_e32 v9, v8
	v_add_f32_e32 v6, v70, v6
	v_cndmask_b32_e32 v133, 0, v6, vcc
	v_readlane_b32 s64, v252, 18
	v_fma_f32 v5, -v8, v9, 1.0
	v_fmac_f32_e32 v9, v5, v9
	v_div_scale_f32 v5, vcc, 1.0, v7, 1.0
	v_mul_f32_e32 v6, v5, v9
	v_readlane_b32 s78, v252, 32
	v_fma_f32 v10, -v8, v6, v5
	v_readlane_b32 s79, v252, 33
	s_add_u32 s27, s78, s8
	v_fmac_f32_e32 v6, v10, v9
	s_addc_u32 s29, s79, s9
	v_fma_f32 v5, -v8, v6, v5
	s_lshl_b32 s3, s2, 14
	v_and_b32_e32 v8, 7, v84
	v_div_fmas_f32 v5, v5, v9, v6
	s_add_u32 s8, s24, s3
	v_readfirstlane_b32 s10, v142
	v_bitop3_b32 v8, v8, v81, v83 bitop3:0x36
	v_lshlrev_b32_e32 v9, 8, v84
	s_addc_u32 s9, s25, 0
	s_lshl_b32 s10, s10, 4
	v_lshl_or_b32 v136, v8, 4, v9
	v_and_b32_e32 v8, 0x60, v142
	v_lshlrev_b32_e32 v9, 3, v142
	v_div_fixup_f32 v134, v5, v7, 1.0
	v_lshlrev_b32_e32 v5, 3, v2
	v_lshlrev_b32_e32 v6, 4, v2
	v_lshlrev_b32_e32 v7, 1, v2
	v_bitop3_b32 v2, v85, v81, v83 bitop3:0x36
	s_and_b32 s10, s10, 0xfffffc00
	v_and_or_b32 v8, v9, 24, v8
	v_bfe_u32 v9, v142, 2, 2
	v_lshrrev_b32_e32 v10, 4, v142
	v_lshl_or_b32 v2, v2, 4, v86
	s_mov_b32 m0, s10
	v_and_or_b32 v9, v79, 4, v9
	v_and_b32_e32 v10, 48, v10
	v_and_b32_e32 v11, 8, v80
	global_load_lds_dwordx4 v2, s[8:9]
	s_add_i32 m0, s10, 0x2000
	v_or3_b32 v9, v9, v10, v11
	global_load_lds_dwordx4 v136, s[8:9]
	s_add_u32 s8, s27, s3
	v_lshlrev_b32_e32 v9, 8, v9
	v_lshlrev_b32_e32 v8, 1, v8
	s_addc_u32 s9, s29, 0
	v_or_b32_e32 v138, v9, v8
	s_add_i32 m0, s10, 0x8000
	s_movk_i32 s3, 0x2000
	global_load_lds_dwordx4 v138, s[8:9]
	v_bitop3_b32 v140, v9, s3, v8 bitop3:0x36
	s_add_i32 m0, s10, 0xa000
	v_and_or_b32 v8, v142, 7, v11
	global_load_lds_dwordx4 v140, s[8:9]
	v_lshlrev_b32_e32 v8, 4, v8
	s_movk_i32 s3, 0x60
	v_bitop3_b32 v150, v8, v76, s3 bitop3:0x1e
	s_movk_i32 s3, 0x80
	v_bitop3_b32 v151, v8, v76, s3 bitop3:0x1e
	s_movk_i32 s3, 0xa0
	v_and_b32_e32 v5, 0x118, v5
	v_bitop3_b32 v152, v8, v76, s3 bitop3:0x1e
	s_movk_i32 s3, 0xc0
	v_and_b32_e32 v6, 0xc0, v6
	v_bitop3_b32 v153, v8, v76, s3 bitop3:0x1e
	s_movk_i32 s3, 0xe0
	v_and_or_b32 v5, v7, 32, v5
	v_bitop3_b32 v154, v8, v76, s3 bitop3:0x1e
	v_or3_b32 v155, v6, v5, s23
	v_lshrrev_b32_e32 v5, 3, v74
	s_movk_i32 s3, 0x2080
	s_lshl_b32 s22, s2, 6
	v_mul_lo_u32 v5, v5, s3
	v_mul_u32_u24_e32 v6, 0x410, v72
	v_add3_u32 v5, v5, v6, s22
	s_lshl_b32 s2, s2, 10
	v_or_b32_e32 v156, v5, v145
	v_subrev_u32_e32 v5, s2, v77
	v_mov_b32_e32 v4, 0
	v_subrev_u32_e32 v157, 31, v5
	v_sub_u32_e32 v5, s2, v73
	s_mov_b32 s26, 0
	v_mov_b32_e32 v137, v3
	v_mov_b32_e32 v139, v3
	v_mov_b32_e32 v141, v3
	v_mul_f32_e32 v146, v132, v78
	v_xor_b32_e32 v147, v8, v76
	v_bitop3_b32 v148, v8, v76, 32 bitop3:0x1e
	v_bitop3_b32 v149, v8, v76, 64 bitop3:0x1e
	v_cmp_eq_u32_e64 s[8:9], 0, v75
	v_mov_b32_e32 v135, v134
	v_add_u32_e32 v158, 31, v5
	s_mov_b32 s52, 0
	s_mov_b32 s53, 0
	v_mov_b32_e32 v5, v4
	v_mov_b32_e32 v6, v4
	v_mov_b32_e32 v7, v4
	v_mov_b32_e32 v8, v4
	v_mov_b32_e32 v9, v4
	v_mov_b32_e32 v10, v4
	v_mov_b32_e32 v11, v4
	v_mov_b32_e32 v12, v4
	v_mov_b32_e32 v13, v4
	v_mov_b32_e32 v14, v4
	v_mov_b32_e32 v15, v4
	v_mov_b32_e32 v16, v4
	v_mov_b32_e32 v17, v4
	v_mov_b32_e32 v18, v4
	v_mov_b32_e32 v19, v4
	v_mov_b32_e32 v52, v4
	v_mov_b32_e32 v53, v4
	v_mov_b32_e32 v54, v4
	v_mov_b32_e32 v55, v4
	v_mov_b32_e32 v56, v4
	v_mov_b32_e32 v57, v4
	v_mov_b32_e32 v58, v4
	v_mov_b32_e32 v59, v4
	v_mov_b32_e32 v60, v4
	v_mov_b32_e32 v61, v4
	v_mov_b32_e32 v62, v4
	v_mov_b32_e32 v63, v4
	v_mov_b32_e32 v64, v4
	v_mov_b32_e32 v65, v4
	v_mov_b32_e32 v66, v4
	v_mov_b32_e32 v67, v4
	v_mov_b32_e32 v36, v4
	v_mov_b32_e32 v37, v4
	v_mov_b32_e32 v38, v4
	v_mov_b32_e32 v39, v4
	v_mov_b32_e32 v40, v4
	v_mov_b32_e32 v41, v4
	v_mov_b32_e32 v42, v4
	v_mov_b32_e32 v43, v4
	v_mov_b32_e32 v44, v4
	v_mov_b32_e32 v45, v4
	v_mov_b32_e32 v46, v4
	v_mov_b32_e32 v47, v4
	v_mov_b32_e32 v48, v4
	v_mov_b32_e32 v49, v4
	v_mov_b32_e32 v50, v4
	v_mov_b32_e32 v51, v4
	v_mov_b32_e32 v20, v4
	v_mov_b32_e32 v21, v4
	v_mov_b32_e32 v22, v4
	v_mov_b32_e32 v23, v4
	v_mov_b32_e32 v24, v4
	v_mov_b32_e32 v25, v4
	v_mov_b32_e32 v26, v4
	v_mov_b32_e32 v27, v4
	v_mov_b32_e32 v28, v4
	v_mov_b32_e32 v29, v4
	v_mov_b32_e32 v30, v4
	v_mov_b32_e32 v31, v4
	v_mov_b32_e32 v32, v4
	v_mov_b32_e32 v33, v4
	v_mov_b32_e32 v34, v4
	v_mov_b32_e32 v35, v4
	v_readlane_b32 s65, v252, 19
	v_readlane_b32 s66, v252, 20
	v_readlane_b32 s67, v252, 21
	v_readlane_b32 s68, v252, 22
	v_readlane_b32 s69, v252, 23
	v_readlane_b32 s70, v252, 24
	v_readlane_b32 s71, v252, 25
	v_readlane_b32 s72, v252, 26
	v_readlane_b32 s73, v252, 27
	v_readlane_b32 s74, v252, 28
	v_readlane_b32 s75, v252, 29
	v_readlane_b32 s76, v252, 30
	v_readlane_b32 s77, v252, 31
	v_mov_b32_e32 v226, 0
	v_mul_f32_e32 v227, 0x40faf232, v132
	v_mul_f32_e32 v228, 0x417af232, v132
	v_mul_f32_e32 v229, 0x41bc35a6, v132
	v_mul_f32_e32 v230, 0x427af232, v132
	v_mul_f32_e32 v231, 0x428d283c, v132
	v_mul_f32_e32 v232, 0x429cd760, v132
	v_mul_f32_e32 v233, 0x42ac8683, v132
	v_mul_f32_e32 v234, 0x42faf232, v132
	v_mul_f32_e32 v235, 0x430550ab, v132
	v_mul_f32_e32 v236, 0x430d283c, v132
	v_mul_f32_e32 v237, 0x4314ffce, v132
	v_mul_f32_e32 v238, 0x433c35a6, v132
	v_mul_f32_e32 v239, 0x43440d37, v132
	v_mul_f32_e32 v240, 0x434be4c9, v132
	v_mul_f32_e32 v241, 0x4353bc5b, v132
	s_branch .LBB0_276

; #define KSWZ(row, colB) ((row) * 256 + ((colB) ^ (KSWZF(row) << 4)))
; #define SBAR() __builtin_amdgcn_sched_barrier(0)
; template <int H> __device__ __forceinline__ void qkt_half(f32x16& pz, const char* Ks, const bf16x8* qr, int r32, int hi) {
;   bf16x8 kf[8];
; #pragma unroll
;   for (int d0 = 0; d0 < 8; ++d0) { const int cb = (d0 * 16 + hi * 8) * 2; kf[d0] = *reinterpret_cast<const bf16x8*>(Ks + KSWZ(32 * H + r32, cb)); }
;   asm volatile("s_waitcnt lgkmcnt(0)" ::: "memory"); SBAR();
;   f32x16 pb = {};
; #pragma unroll
;   for (int d0 = 0; d0 < 8; d0 += 2) {
;     pz = __builtin_amdgcn_mfma_f32_32x32x16_bf16(kf[d0], qr[d0], pz, 0, 0, 0);
;     pb = __builtin_amdgcn_mfma_f32_32x32x16_bf16(kf[d0 + 1], qr[d0 + 1], pb, 0, 0, 0); }
; #pragma unroll
;   for (int r = 0; r < 16; ++r) pz[r] += pb[r];
; }
; template <bool MASK, int H> __device__ __forceinline__ void bias_exp_half(f32x16& pz, float C, float A1, float B1, int lo, int hl, float off) {
; #pragma unroll
;   for (int r = 0; r < 16; ++r) {
;     const int c0 = (r & 3) + 8 * (r >> 2) + 32 * H;
;     float s0 = fmaf(pz[r], C, fmaf(A1, (float)c0, B1)) - off;
;     if (MASK) s0 = (c0 > lo && c0 <= hl) ? s0 : -INFINITY;
;     pz[r] = __builtin_amdgcn_exp2f(s0);
;   }
; }
.LBB0_278:
	v_cvt_f32_i32_e32 v68, v158
	v_ashrrev_i32_e32 v69, 4, v157
	v_sub_u32_e32 v160, v69, v145
	v_fma_f32 v159, v143, v68, v146
	v_cmp_lt_i32_e32 vcc, 62, v160
	s_nop 3
	s_cmp_lg_u64 vcc, exec
	s_cselect_b64 s[98:99], -1, 0
	v_add_u32_e32 v248, s28, v144
	v_add_u32_e32 v249, v248, v147
	ds_read_b128 v[84:87], v249
	v_add_u32_e32 v251, v248, v148
	ds_read_b128 v[88:91], v251
	v_add_u32_e32 v249, v248, v149
	ds_read_b128 v[92:95], v249
	v_add_u32_e32 v251, v248, v150
	ds_read_b128 v[96:99], v251
	v_add_u32_e32 v249, v248, v151
	ds_read_b128 v[194:197], v249
	v_add_u32_e32 v251, v248, v152
	ds_read_b128 v[198:201], v251
	v_add_u32_e32 v249, v248, v153
	ds_read_b128 v[202:205], v249
	v_add_u32_e32 v251, v248, v154
	ds_read_b128 v[206:209], v251
	s_nop 0
	v_add_u32_e32 v248, s28, v155
	v_mov_b32_e32 v250, v159
	s_waitcnt lgkmcnt(0)
	v_mfma_f32_32x32x16_bf16 v[68:83], v[84:87], v[100:103], v[226:241]
	v_mfma_f32_32x32x16_bf16 v[68:83], v[88:91], v[104:107], v[68:83]
	v_mfma_f32_32x32x16_bf16 v[68:83], v[92:95], v[108:111], v[68:83]
	v_mfma_f32_32x32x16_bf16 v[68:83], v[96:99], v[112:115], v[68:83]
	v_mfma_f32_32x32x16_bf16 v[68:83], v[194:197], v[116:119], v[68:83]
	v_mfma_f32_32x32x16_bf16 v[68:83], v[198:201], v[120:123], v[68:83]
	v_mfma_f32_32x32x16_bf16 v[68:83], v[202:205], v[124:127], v[68:83]
	v_mfma_f32_32x32x16_bf16 v[68:83], v[206:209], v[128:131], v[68:83]
	ds_read_b64_tr_b16 v[84:85], v248 offset:0
	ds_read_b64_tr_b16 v[86:87], v248 offset:2048
	ds_read_b64_tr_b16 v[88:89], v248 offset:4096
	ds_read_b64_tr_b16 v[90:91], v248 offset:6144
	ds_read_b64_tr_b16 v[92:93], v248 offset:512
	ds_read_b64_tr_b16 v[94:95], v248 offset:2560
	ds_read_b64_tr_b16 v[96:97], v248 offset:4608
	ds_read_b64_tr_b16 v[98:99], v248 offset:6656
	ds_read_b64_tr_b16 v[194:195], v248 offset:1024
	ds_read_b64_tr_b16 v[196:197], v248 offset:3072
	ds_read_b64_tr_b16 v[198:199], v248 offset:5120
	ds_read_b64_tr_b16 v[200:201], v248 offset:7168
	ds_read_b64_tr_b16 v[202:203], v248 offset:1536
	ds_read_b64_tr_b16 v[204:205], v248 offset:3584
	ds_read_b64_tr_b16 v[206:207], v248 offset:5632
	ds_read_b64_tr_b16 v[208:209], v248 offset:7680
	v_sub_f32_e32 v251, v250, v133
	s_and_b64 vcc, exec, s[98:99]
	s_cbranch_vccz .Lpb_nm0
	v_cmp_lt_i32_e32 vcc, -1, v160
	v_cmp_lt_i32_e64 s[10:11], 0, v160
	v_cmp_lt_i32_e64 s[12:13], 1, v160
	v_cmp_lt_i32_e64 s[2:3], 2, v160
	s_nop 0
	v_cndmask_b32_e32 v68, v183, v68, vcc
	v_cndmask_b32_e64 v69, v183, v69, s[10:11]
	v_cndmask_b32_e64 v70, v183, v70, s[12:13]
	v_cndmask_b32_e64 v71, v183, v71, s[2:3]
	v_cmp_lt_i32_e32 vcc, 7, v160
	v_cmp_lt_i32_e64 s[10:11], 8, v160
	v_cmp_lt_i32_e64 s[12:13], 9, v160
	v_cmp_lt_i32_e64 s[2:3], 10, v160
	s_nop 0
	v_cndmask_b32_e32 v72, v183, v72, vcc
	v_cndmask_b32_e64 v73, v183, v73, s[10:11]
	v_cndmask_b32_e64 v74, v183, v74, s[12:13]
	v_cndmask_b32_e64 v75, v183, v75, s[2:3]
	v_cmp_lt_i32_e32 vcc, 15, v160
	v_cmp_lt_i32_e64 s[10:11], 16, v160
	v_cmp_lt_i32_e64 s[12:13], 17, v160
	v_cmp_lt_i32_e64 s[2:3], 18, v160
	s_nop 0
	v_cndmask_b32_e32 v76, v183, v76, vcc
	v_cndmask_b32_e64 v77, v183, v77, s[10:11]
	v_cndmask_b32_e64 v78, v183, v78, s[12:13]
	v_cndmask_b32_e64 v79, v183, v79, s[2:3]
	v_cmp_lt_i32_e32 vcc, 23, v160
	v_cmp_lt_i32_e64 s[10:11], 24, v160
	v_cmp_lt_i32_e64 s[12:13], 25, v160
	v_cmp_lt_i32_e64 s[2:3], 26, v160
	s_nop 0
	v_cndmask_b32_e32 v80, v183, v80, vcc
	v_cndmask_b32_e64 v81, v183, v81, s[10:11]
	v_cndmask_b32_e64 v82, v183, v82, s[12:13]
	v_cndmask_b32_e64 v83, v183, v83, s[2:3]
.Lpb_nm0:
	v_fmamk_f32 v68, v68, 0x3e0293ee, v251
	v_fmamk_f32 v69, v69, 0x3e0293ee, v251
	v_fmamk_f32 v70, v70, 0x3e0293ee, v251
	v_fmamk_f32 v71, v71, 0x3e0293ee, v251
	v_fmamk_f32 v72, v72, 0x3e0293ee, v251
	v_fmamk_f32 v73, v73, 0x3e0293ee, v251
	v_fmamk_f32 v74, v74, 0x3e0293ee, v251
	v_fmamk_f32 v75, v75, 0x3e0293ee, v251
	v_fmamk_f32 v76, v76, 0x3e0293ee, v251
	v_fmamk_f32 v77, v77, 0x3e0293ee, v251
	v_fmamk_f32 v78, v78, 0x3e0293ee, v251
	v_fmamk_f32 v79, v79, 0x3e0293ee, v251
	v_fmamk_f32 v80, v80, 0x3e0293ee, v251
	v_fmamk_f32 v81, v81, 0x3e0293ee, v251
	v_fmamk_f32 v82, v82, 0x3e0293ee, v251
	v_fmamk_f32 v83, v83, 0x3e0293ee, v251
	v_exp_f32_e32 v68, v68
	v_exp_f32_e32 v69, v69
	v_exp_f32_e32 v70, v70
	v_exp_f32_e32 v71, v71
	v_exp_f32_e32 v72, v72
	v_exp_f32_e32 v73, v73
	v_exp_f32_e32 v74, v74
	v_exp_f32_e32 v75, v75
	v_exp_f32_e32 v76, v76
	v_exp_f32_e32 v77, v77
	v_exp_f32_e32 v78, v78
	v_exp_f32_e32 v79, v79
	v_exp_f32_e32 v80, v80
	v_exp_f32_e32 v81, v81
	v_exp_f32_e32 v82, v82
	v_exp_f32_e32 v83, v83
	s_nop 0
	v_add_f32_e32 v242, v68, v69
	v_add_f32_e32 v243, v72, v73
	v_add_f32_e32 v244, v76, v77
	v_add_f32_e32 v245, v80, v81
	v_add_f32_e32 v242, v70, v242
	v_add_f32_e32 v243, v74, v243
	v_add_f32_e32 v244, v78, v244
	v_add_f32_e32 v245, v82, v245
	v_add_f32_e32 v242, v71, v242
	v_add_f32_e32 v243, v75, v243
	v_add_f32_e32 v244, v79, v244
	v_add_f32_e32 v245, v83, v245
	v_add_u32_e32 v251, s52, v156
	s_nop 0
	v_add_f32_dpp v246, v71, v71 quad_perm:[1,0,3,2] row_mask:0xf bank_mask:0xf bound_ctrl:1
	v_add_f32_dpp v247, v75, v75 quad_perm:[1,0,3,2] row_mask:0xf bank_mask:0xf bound_ctrl:1
	v_add_f32_dpp v248, v79, v79 quad_perm:[1,0,3,2] row_mask:0xf bank_mask:0xf bound_ctrl:1
	v_add_f32_dpp v249, v83, v83 quad_perm:[1,0,3,2] row_mask:0xf bank_mask:0xf bound_ctrl:1
	v_add_f32_dpp v242, v242, v242 quad_perm:[1,0,3,2] row_mask:0xf bank_mask:0xf bound_ctrl:1
	v_add_f32_dpp v243, v243, v243 quad_perm:[1,0,3,2] row_mask:0xf bank_mask:0xf bound_ctrl:1
	v_add_f32_dpp v244, v244, v244 quad_perm:[1,0,3,2] row_mask:0xf bank_mask:0xf bound_ctrl:1
; #define SBAR() __builtin_amdgcn_sched_barrier(0)
; #define TRQ(D0) const s16x4 l0_##D0 = tr_read<v_rd_off(D0, 2 * H, 0)>(vb), h0_##D0 = tr_read<v_rd_off(D0, 2 * H, 1)>(vb), \
;                             l1_##D0 = tr_read<v_rd_off(D0, 2 * H + 1, 0)>(vb), h1_##D0 = tr_read<v_rd_off(D0, 2 * H + 1, 1)>(vb)
; template <int H> __device__ __forceinline__ void pv_half(f32x16* o, int vb, bf16x8 paA, bf16x8 paB) {
;     ...
;   TRQ(0); TRQ(1); TRQ(2); TRQ(3);
;     ...
;   asm volatile("s_waitcnt lgkmcnt(0)" ::: "memory"); SBAR();
;     ...
;   o[0] = __builtin_amdgcn_mfma_f32_32x32x16_bf16(paA, PK(l0_0, h0_0), o[0], 0, 0, 0);
;   o[1] = __builtin_amdgcn_mfma_f32_32x32x16_bf16(paA, PK(l0_1, h0_1), o[1], 0, 0, 0);
;   o[2] = __builtin_amdgcn_mfma_f32_32x32x16_bf16(paA, PK(l0_2, h0_2), o[2], 0, 0, 0);
;   o[3] = __builtin_amdgcn_mfma_f32_32x32x16_bf16(paA, PK(l0_3, h0_3), o[3], 0, 0, 0);
;   o[0] = __builtin_amdgcn_mfma_f32_32x32x16_bf16(paB, PK(l1_0, h1_0), o[0], 0, 0, 0);
;   o[1] = __builtin_amdgcn_mfma_f32_32x32x16_bf16(paB, PK(l1_1, h1_1), o[1], 0, 0, 0);
;   o[2] = __builtin_amdgcn_mfma_f32_32x32x16_bf16(paB, PK(l1_2, h1_2), o[2], 0, 0, 0);
;   o[3] = __builtin_amdgcn_mfma_f32_32x32x16_bf16(paB, PK(l1_3, h1_3), o[3], 0, 0, 0);
;     ...
; }
; template <int MODE, bool PB>
; __device__ __forceinline__ void nsa_pass(const Params& p, const LaneId& L, int q0, int g, int ntiles, int first, char* smem, const bf16x8* qr,
;                                          float& m, float& l, float off, float gate0, f32x16* o) {
;     ...
;       NSA_HALF(0);
;       NSA_HALF(1);
	v_add_f32_dpp v245, v245, v245 quad_perm:[1,0,3,2] row_mask:0xf bank_mask:0xf bound_ctrl:1
	v_add_u32_e32 v251, 0x10000, v251
	s_nop 0
	v_add_f32_dpp v172, v246, v246 quad_perm:[2,3,0,1] row_mask:0xf bank_mask:0xf bound_ctrl:1
	v_add_f32_dpp v173, v247, v247 quad_perm:[2,3,0,1] row_mask:0xf bank_mask:0xf bound_ctrl:1
	v_add_f32_dpp v174, v248, v248 quad_perm:[2,3,0,1] row_mask:0xf bank_mask:0xf bound_ctrl:1
	v_add_f32_dpp v175, v249, v249 quad_perm:[2,3,0,1] row_mask:0xf bank_mask:0xf bound_ctrl:1
	v_add_f32_dpp v168, v242, v242 quad_perm:[2,3,0,1] row_mask:0xf bank_mask:0xf bound_ctrl:1
	v_add_f32_dpp v169, v243, v243 quad_perm:[2,3,0,1] row_mask:0xf bank_mask:0xf bound_ctrl:1
	v_add_f32_dpp v170, v244, v244 quad_perm:[2,3,0,1] row_mask:0xf bank_mask:0xf bound_ctrl:1
	v_add_f32_dpp v171, v245, v245 quad_perm:[2,3,0,1] row_mask:0xf bank_mask:0xf bound_ctrl:1
	s_and_saveexec_b64 s[2:3], s[8:9]
	ds_add_f32 v251, v168 offset:0
	ds_add_f32 v251, v172 offset:4
	ds_add_f32 v251, v169 offset:8
	ds_add_f32 v251, v173 offset:12
	ds_add_f32 v251, v170 offset:16
	ds_add_f32 v251, v174 offset:20
	ds_add_f32 v251, v171 offset:24
	ds_add_f32 v251, v175 offset:28
	s_or_b64 exec, exec, s[2:3]
	v_mul_f32_e32 v68, v134, v68
	v_mul_f32_e32 v69, v134, v69
	v_mul_f32_e32 v70, v134, v70
	v_mul_f32_e32 v71, v134, v71
	v_mul_f32_e32 v72, v134, v72
	v_mul_f32_e32 v73, v134, v73
	v_mul_f32_e32 v74, v134, v74
	v_mul_f32_e32 v75, v134, v75
	v_mul_f32_e32 v76, v134, v76
	v_mul_f32_e32 v77, v134, v77
	v_mul_f32_e32 v78, v134, v78
	v_mul_f32_e32 v79, v134, v79
	v_mul_f32_e32 v80, v134, v80
	v_mul_f32_e32 v81, v134, v81
	v_mul_f32_e32 v82, v134, v82
	v_mul_f32_e32 v83, v134, v83
	v_cvt_pk_bf16_f32 v168, v68, v69
	v_cvt_pk_bf16_f32 v169, v70, v71
	v_cvt_pk_bf16_f32 v170, v72, v73
	v_cvt_pk_bf16_f32 v171, v74, v75
	v_cvt_pk_bf16_f32 v172, v76, v77
	v_cvt_pk_bf16_f32 v173, v78, v79
	v_cvt_pk_bf16_f32 v174, v80, v81
	v_cvt_pk_bf16_f32 v175, v82, v83
	s_waitcnt lgkmcnt(0)
	s_nop 1
	v_permlane32_swap_b32_e32 v168, v170
	v_permlane32_swap_b32_e32 v169, v171
	v_permlane32_swap_b32_e32 v172, v174
	v_permlane32_swap_b32_e32 v173, v175
	s_nop 1
	v_mfma_f32_32x32x16_bf16 v[4:19], v[168:171], v[84:87], v[4:19]
	v_mfma_f32_32x32x16_bf16 v[52:67], v[168:171], v[92:95], v[52:67]
	v_mfma_f32_32x32x16_bf16 v[36:51], v[168:171], v[194:197], v[36:51]
	v_mfma_f32_32x32x16_bf16 v[20:35], v[168:171], v[202:205], v[20:35]
	v_mfma_f32_32x32x16_bf16 v[4:19], v[172:175], v[88:91], v[4:19]
	v_mfma_f32_32x32x16_bf16 v[52:67], v[172:175], v[96:99], v[52:67]
	v_mfma_f32_32x32x16_bf16 v[36:51], v[172:175], v[198:201], v[36:51]
	v_mfma_f32_32x32x16_bf16 v[20:35], v[172:175], v[206:209], v[20:35]
	v_add_u32_e32 v248, s28, v144
	v_add_u32_e32 v249, v248, v147
	ds_read_b128 v[84:87], v249 offset:8192
	v_add_u32_e32 v251, v248, v148
	ds_read_b128 v[88:91], v251 offset:8192
	v_add_u32_e32 v249, v248, v149
	ds_read_b128 v[92:95], v249 offset:8192
	v_add_u32_e32 v251, v248, v150
	ds_read_b128 v[96:99], v251 offset:8192
	v_add_u32_e32 v249, v248, v151
	ds_read_b128 v[194:197], v249 offset:8192
	v_add_u32_e32 v251, v248, v152
	ds_read_b128 v[198:201], v251 offset:8192
	v_add_u32_e32 v249, v248, v153
	ds_read_b128 v[202:205], v249 offset:8192
	v_add_u32_e32 v251, v248, v154
	ds_read_b128 v[206:209], v251 offset:8192
	s_nop 0
	v_add_u32_e32 v248, s28, v155
	v_fmamk_f32 v250, v132, 0x42000000, v159
	s_waitcnt lgkmcnt(0)
	v_mfma_f32_32x32x16_bf16 v[68:83], v[84:87], v[100:103], v[226:241]
	v_mfma_f32_32x32x16_bf16 v[68:83], v[88:91], v[104:107], v[68:83]
	v_mfma_f32_32x32x16_bf16 v[68:83], v[92:95], v[108:111], v[68:83]
	v_mfma_f32_32x32x16_bf16 v[68:83], v[96:99], v[112:115], v[68:83]
	v_mfma_f32_32x32x16_bf16 v[68:83], v[194:197], v[116:119], v[68:83]
	v_mfma_f32_32x32x16_bf16 v[68:83], v[198:201], v[120:123], v[68:83]
	v_mfma_f32_32x32x16_bf16 v[68:83], v[202:205], v[124:127], v[68:83]
	v_mfma_f32_32x32x16_bf16 v[68:83], v[206:209], v[128:131], v[68:83]
	ds_read_b64_tr_b16 v[84:85], v248 offset:8192
	ds_read_b64_tr_b16 v[86:87], v248 offset:10240
	ds_read_b64_tr_b16 v[88:89], v248 offset:12288
	ds_read_b64_tr_b16 v[90:91], v248 offset:14336
	ds_read_b64_tr_b16 v[92:93], v248 offset:8704
	ds_read_b64_tr_b16 v[94:95], v248 offset:10752
	ds_read_b64_tr_b16 v[96:97], v248 offset:12800
	ds_read_b64_tr_b16 v[98:99], v248 offset:14848
	ds_read_b64_tr_b16 v[194:195], v248 offset:9216
	ds_read_b64_tr_b16 v[196:197], v248 offset:11264
	ds_read_b64_tr_b16 v[198:199], v248 offset:13312
	ds_read_b64_tr_b16 v[200:201], v248 offset:15360
	ds_read_b64_tr_b16 v[202:203], v248 offset:9728
	ds_read_b64_tr_b16 v[204:205], v248 offset:11776
	ds_read_b64_tr_b16 v[206:207], v248 offset:13824
	ds_read_b64_tr_b16 v[208:209], v248 offset:15872
	v_sub_f32_e32 v251, v250, v133
	s_and_b64 vcc, exec, s[98:99]
	s_cbranch_vccz .Lpb_nm1
	v_cmp_lt_i32_e32 vcc, 31, v160
	v_cmp_lt_i32_e64 s[10:11], 32, v160
	v_cmp_lt_i32_e64 s[12:13], 33, v160
	v_cmp_lt_i32_e64 s[2:3], 34, v160
	s_nop 0
	v_cndmask_b32_e32 v68, v183, v68, vcc
	v_cndmask_b32_e64 v69, v183, v69, s[10:11]
	v_cndmask_b32_e64 v70, v183, v70, s[12:13]
	v_cndmask_b32_e64 v71, v183, v71, s[2:3]
	v_cmp_lt_i32_e32 vcc, 39, v160
	v_cmp_lt_i32_e64 s[10:11], 40, v160
	v_cmp_lt_i32_e64 s[12:13], 41, v160
	v_cmp_lt_i32_e64 s[2:3], 42, v160
	s_nop 0
	v_cndmask_b32_e32 v72, v183, v72, vcc
	v_cndmask_b32_e64 v73, v183, v73, s[10:11]
	v_cndmask_b32_e64 v74, v183, v74, s[12:13]
	v_cndmask_b32_e64 v75, v183, v75, s[2:3]
	v_cmp_lt_i32_e32 vcc, 47, v160
	v_cmp_lt_i32_e64 s[10:11], 48, v160
	v_cmp_lt_i32_e64 s[12:13], 49, v160
	v_cmp_lt_i32_e64 s[2:3], 50, v160
	s_nop 0
	v_cndmask_b32_e32 v76, v183, v76, vcc
	v_cndmask_b32_e64 v77, v183, v77, s[10:11]
	v_cndmask_b32_e64 v78, v183, v78, s[12:13]
	v_cndmask_b32_e64 v79, v183, v79, s[2:3]
	v_cmp_lt_i32_e32 vcc, 55, v160
	v_cmp_lt_i32_e64 s[10:11], 56, v160
	v_cmp_lt_i32_e64 s[12:13], 57, v160
	v_cmp_lt_i32_e64 s[2:3], 58, v160
	s_nop 0
	v_cndmask_b32_e32 v80, v183, v80, vcc
	v_cndmask_b32_e64 v81, v183, v81, s[10:11]
	v_cndmask_b32_e64 v82, v183, v82, s[12:13]
	v_cndmask_b32_e64 v83, v183, v83, s[2:3]
; #define SBAR() __builtin_amdgcn_sched_barrier(0)
; #define TRQ(D0) const s16x4 l0_##D0 = tr_read<v_rd_off(D0, 2 * H, 0)>(vb), h0_##D0 = tr_read<v_rd_off(D0, 2 * H, 1)>(vb), \
;                             l1_##D0 = tr_read<v_rd_off(D0, 2 * H + 1, 0)>(vb), h1_##D0 = tr_read<v_rd_off(D0, 2 * H + 1, 1)>(vb)
; template <int H> __device__ __forceinline__ void pv_half(f32x16* o, int vb, bf16x8 paA, bf16x8 paB) {
;     ...
;   TRQ(0); TRQ(1); TRQ(2); TRQ(3);
;     ...
;   asm volatile("s_waitcnt lgkmcnt(0)" ::: "memory"); SBAR();
;     ...
;   o[0] = __builtin_amdgcn_mfma_f32_32x32x16_bf16(paA, PK(l0_0, h0_0), o[0], 0, 0, 0);
;   o[1] = __builtin_amdgcn_mfma_f32_32x32x16_bf16(paA, PK(l0_1, h0_1), o[1], 0, 0, 0);
;   o[2] = __builtin_amdgcn_mfma_f32_32x32x16_bf16(paA, PK(l0_2, h0_2), o[2], 0, 0, 0);
;   o[3] = __builtin_amdgcn_mfma_f32_32x32x16_bf16(paA, PK(l0_3, h0_3), o[3], 0, 0, 0);
;   o[0] = __builtin_amdgcn_mfma_f32_32x32x16_bf16(paB, PK(l1_0, h1_0), o[0], 0, 0, 0);
;   o[1] = __builtin_amdgcn_mfma_f32_32x32x16_bf16(paB, PK(l1_1, h1_1), o[1], 0, 0, 0);
;   o[2] = __builtin_amdgcn_mfma_f32_32x32x16_bf16(paB, PK(l1_2, h1_2), o[2], 0, 0, 0);
;   o[3] = __builtin_amdgcn_mfma_f32_32x32x16_bf16(paB, PK(l1_3, h1_3), o[3], 0, 0, 0);
;     ...
; }
; template <int MODE, bool PB>
; __device__ __forceinline__ void nsa_pass(const Params& p, const LaneId& L, int q0, int g, int ntiles, int first, char* smem, const bf16x8* qr,
;                                          float& m, float& l, float off, float gate0, f32x16* o) {
;     ...
;       NSA_HALF(0);
;       NSA_HALF(1);
.Lpb_nm1:
	v_fmamk_f32 v68, v68, 0x3e0293ee, v251
	v_fmamk_f32 v69, v69, 0x3e0293ee, v251
	v_fmamk_f32 v70, v70, 0x3e0293ee, v251
	v_fmamk_f32 v71, v71, 0x3e0293ee, v251
	v_fmamk_f32 v72, v72, 0x3e0293ee, v251
	v_fmamk_f32 v73, v73, 0x3e0293ee, v251
	v_fmamk_f32 v74, v74, 0x3e0293ee, v251
	v_fmamk_f32 v75, v75, 0x3e0293ee, v251
	v_fmamk_f32 v76, v76, 0x3e0293ee, v251
	v_fmamk_f32 v77, v77, 0x3e0293ee, v251
	v_fmamk_f32 v78, v78, 0x3e0293ee, v251
	v_fmamk_f32 v79, v79, 0x3e0293ee, v251
	v_fmamk_f32 v80, v80, 0x3e0293ee, v251
	v_fmamk_f32 v81, v81, 0x3e0293ee, v251
	v_fmamk_f32 v82, v82, 0x3e0293ee, v251
	v_fmamk_f32 v83, v83, 0x3e0293ee, v251
	v_exp_f32_e32 v68, v68
	v_exp_f32_e32 v69, v69
	v_exp_f32_e32 v70, v70
	v_exp_f32_e32 v71, v71
	v_exp_f32_e32 v72, v72
	v_exp_f32_e32 v73, v73
	v_exp_f32_e32 v74, v74
	v_exp_f32_e32 v75, v75
	v_exp_f32_e32 v76, v76
	v_exp_f32_e32 v77, v77
	v_exp_f32_e32 v78, v78
	v_exp_f32_e32 v79, v79
	v_exp_f32_e32 v80, v80
	v_exp_f32_e32 v81, v81
	v_exp_f32_e32 v82, v82
	v_exp_f32_e32 v83, v83
	s_nop 0
	v_add_f32_e32 v242, v68, v69
	v_add_f32_e32 v243, v72, v73
	v_add_f32_e32 v244, v76, v77
	v_add_f32_e32 v245, v80, v81
	v_add_f32_e32 v242, v70, v242
	v_add_f32_e32 v243, v74, v243
	v_add_f32_e32 v244, v78, v244
	v_add_f32_e32 v245, v82, v245
	v_add_f32_e32 v242, v71, v242
	v_add_f32_e32 v243, v75, v243
	v_add_f32_e32 v244, v79, v244
	v_add_f32_e32 v245, v83, v245
	v_add_u32_e32 v251, s52, v156
	s_nop 0
	v_add_f32_dpp v246, v71, v71 quad_perm:[1,0,3,2] row_mask:0xf bank_mask:0xf bound_ctrl:1
	v_add_f32_dpp v247, v75, v75 quad_perm:[1,0,3,2] row_mask:0xf bank_mask:0xf bound_ctrl:1
	v_add_f32_dpp v248, v79, v79 quad_perm:[1,0,3,2] row_mask:0xf bank_mask:0xf bound_ctrl:1
	v_add_f32_dpp v249, v83, v83 quad_perm:[1,0,3,2] row_mask:0xf bank_mask:0xf bound_ctrl:1
	v_add_f32_dpp v242, v242, v242 quad_perm:[1,0,3,2] row_mask:0xf bank_mask:0xf bound_ctrl:1
	v_add_f32_dpp v243, v243, v243 quad_perm:[1,0,3,2] row_mask:0xf bank_mask:0xf bound_ctrl:1
	v_add_f32_dpp v244, v244, v244 quad_perm:[1,0,3,2] row_mask:0xf bank_mask:0xf bound_ctrl:1
	v_add_f32_dpp v245, v245, v245 quad_perm:[1,0,3,2] row_mask:0xf bank_mask:0xf bound_ctrl:1
	v_add_u32_e32 v251, 0x10000, v251
	s_nop 0
	v_add_f32_dpp v172, v246, v246 quad_perm:[2,3,0,1] row_mask:0xf bank_mask:0xf bound_ctrl:1
	v_add_f32_dpp v173, v247, v247 quad_perm:[2,3,0,1] row_mask:0xf bank_mask:0xf bound_ctrl:1
	v_add_f32_dpp v174, v248, v248 quad_perm:[2,3,0,1] row_mask:0xf bank_mask:0xf bound_ctrl:1
	v_add_f32_dpp v175, v249, v249 quad_perm:[2,3,0,1] row_mask:0xf bank_mask:0xf bound_ctrl:1
	v_add_f32_dpp v168, v242, v242 quad_perm:[2,3,0,1] row_mask:0xf bank_mask:0xf bound_ctrl:1
	v_add_f32_dpp v169, v243, v243 quad_perm:[2,3,0,1] row_mask:0xf bank_mask:0xf bound_ctrl:1
	v_add_f32_dpp v170, v244, v244 quad_perm:[2,3,0,1] row_mask:0xf bank_mask:0xf bound_ctrl:1
	v_add_f32_dpp v171, v245, v245 quad_perm:[2,3,0,1] row_mask:0xf bank_mask:0xf bound_ctrl:1
	s_and_saveexec_b64 s[2:3], s[8:9]
	ds_add_f32 v251, v168 offset:32
	ds_add_f32 v251, v172 offset:36
	ds_add_f32 v251, v169 offset:40
	ds_add_f32 v251, v173 offset:44
	ds_add_f32 v251, v170 offset:48
	ds_add_f32 v251, v174 offset:52
	ds_add_f32 v251, v171 offset:56
	ds_add_f32 v251, v175 offset:60
	s_or_b64 exec, exec, s[2:3]
	v_mul_f32_e32 v68, v134, v68
	v_mul_f32_e32 v69, v134, v69
	v_mul_f32_e32 v70, v134, v70
	v_mul_f32_e32 v71, v134, v71
	v_mul_f32_e32 v72, v134, v72
	v_mul_f32_e32 v73, v134, v73
	v_mul_f32_e32 v74, v134, v74
	v_mul_f32_e32 v75, v134, v75
	v_mul_f32_e32 v76, v134, v76
	v_mul_f32_e32 v77, v134, v77
	v_mul_f32_e32 v78, v134, v78
	v_mul_f32_e32 v79, v134, v79
	v_mul_f32_e32 v80, v134, v80
	v_mul_f32_e32 v81, v134, v81
	v_mul_f32_e32 v82, v134, v82
	v_mul_f32_e32 v83, v134, v83
	v_cvt_pk_bf16_f32 v168, v68, v69
	v_cvt_pk_bf16_f32 v169, v70, v71
	v_cvt_pk_bf16_f32 v170, v72, v73
	v_cvt_pk_bf16_f32 v171, v74, v75
	v_cvt_pk_bf16_f32 v172, v76, v77
	v_cvt_pk_bf16_f32 v173, v78, v79
	v_cvt_pk_bf16_f32 v174, v80, v81
	v_cvt_pk_bf16_f32 v175, v82, v83
	s_waitcnt lgkmcnt(0)
	s_nop 1
	v_permlane32_swap_b32_e32 v168, v170
	v_permlane32_swap_b32_e32 v169, v171
	v_permlane32_swap_b32_e32 v172, v174
	v_permlane32_swap_b32_e32 v173, v175
	s_nop 1
	v_mfma_f32_32x32x16_bf16 v[4:19], v[168:171], v[84:87], v[4:19]
	v_mfma_f32_32x32x16_bf16 v[52:67], v[168:171], v[92:95], v[52:67]
	v_mfma_f32_32x32x16_bf16 v[36:51], v[168:171], v[194:197], v[36:51]
	v_mfma_f32_32x32x16_bf16 v[20:35], v[168:171], v[202:205], v[20:35]
	v_mfma_f32_32x32x16_bf16 v[4:19], v[172:175], v[88:91], v[4:19]
	v_mfma_f32_32x32x16_bf16 v[52:67], v[172:175], v[96:99], v[52:67]
	v_mfma_f32_32x32x16_bf16 v[36:51], v[172:175], v[198:201], v[36:51]
	v_mfma_f32_32x32x16_bf16 v[20:35], v[172:175], v[206:209], v[20:35]
	s_add_i32 s52, s52, 64
	s_addk_i32 s26, 0x4000
	v_add_u32_e32 v157, 0xfffffc00, v157
	v_add_u32_e32 v158, 0x400, v158
	s_cmp_eq_u32 s0, s53
	s_cbranch_scc1 .LBB0_302
	s_branch .LBB0_276
